# baseline (speedup 1.0000x reference)
;     __device__ __forceinline__ void operator()(const pg8::f32x4 (&acc)[2][2][4][2], const pg8::Unit& u, int wr, int wc, int fr, int fq) const {
;         const int row0 = u.pm * 256 + wr * 64 + fr, col0 = u.pn * 256 + wc * 32 + 8 * fq;
;         if (mode >= 5) {
;             const bool hasF = mode == 5, outF = mode == 7;
;             u32x4 cb2 = {0u, 0u, 0u, 0u}, nb2 = cb2, cbb, nbb; float csc, nsc = 1.f, ss = 0.f;
;             {
;                 if (hasF) cb2 = *(const u32x4*)(base2 + (size_t)row0 * 1024 + col0);
;                 cbb = *(const u32x4*)(baseb + (size_t)row0 * 1024 + col0);
;                 csc = rowscale(row0);
;             }
;             nbb = cbb;
; #pragma unroll
;             for (int p = 0; p < 16; ++p) {
;                 const int g = p >> 1, bj = p & 1, ai = g >> 2, m = g & 3, r = row0 + ai * 128 + m * 16, c = col0 + bj * 128;
;                 if (p < 15) {
;                     const int gn = (p + 1) >> 1, rn = row0 + (gn >> 2) * 128 + (gn & 3) * 16, cn = col0 + ((p + 1) & 1) * 128;
;                     if (hasF) nb2 = *(const u32x4*)(base2 + (size_t)rn * 1024 + cn);
;                     nbb = *(const u32x4*)(baseb + (size_t)rn * 1024 + cn);
;                     if (bj == 1) nsc = rowscale(rn);
;                 }
;                 const f32x4 r0 = {bflo(cbb.x), bfhi(cbb.x), bflo(cbb.y), bfhi(cbb.y)}, r1 = {bflo(cbb.z), bfhi(cbb.z), bflo(cbb.w), bfhi(cbb.w)};
;                 const f32x4 q0 = {bflo(cb2.x), bfhi(cb2.x), bflo(cb2.y), bfhi(cb2.y)}, q1 = {bflo(cb2.z), bfhi(cb2.z), bflo(cb2.w), bfhi(cb2.w)};
;                 const f32x4 v0 = acc[ai][bj][m][0] * csc + q0 + r0, v1 = acc[ai][bj][m][1] * csc + q1 + r1;
;                 if (outF) {
;                     float* op = out + (size_t)r * 1024 + c;
;                     *(f32x4*)op = v0; *(f32x4*)(op + 4) = v1;
;                 } else {
;                     u32x4 w; w.x = pk2(v0[0], v0[1]); w.y = pk2(v0[2], v0[3]); w.z = pk2(v1[0], v1[1]); w.w = pk2(v1[2], v1[3]);
;                     *(u32x4*)(O + (size_t)r * 1024 + c) = w;
;                     ss += (v0[0] * v0[0] + v0[1] * v0[1]) + (v0[2] * v0[2] + v0[3] * v0[3]) + (v1[0] * v1[0] + v1[1] * v1[1]) + (v1[2] * v1[2] + v1[3] * v1[3]);
;                     if (bj == 1) {
;                         ss += __shfl_xor(ss, 16); ss += __shfl_xor(ss, 32);
.LBB0_1038:
	v_lshl_add_u32 v144, s16, 8, v148
	v_lshl_or_b32 v162, s39, 8, v150
	v_ashrrev_i32_e32 v145, 31, v144
	v_lshlrev_b64 v[146:147], 11, v[144:145]
	v_ashrrev_i32_e32 v163, 31, v162
	v_lshl_add_u64 v[154:155], s[78:79], 0, v[146:147]
	v_lshlrev_b64 v[146:147], 1, v[162:163]
	v_lshl_add_u64 v[158:159], v[154:155], 0, v[146:147]
	global_load_dwordx4 v[154:157], v[158:159], off nt
	s_nop 0
	global_load_dwordx4 v[158:161], v[158:159], off offset:256 nt
	v_or_b32_e32 v174, 16, v144
	v_pk_add_f32 v[170:171], v[114:115], 0 op_sel_hi:[1,0]
	v_lshlrev_b64 v[114:115], 12, v[144:145]
	v_ashrrev_i32_e32 v175, 31, v174
	v_pk_add_f32 v[168:169], v[116:117], 0 op_sel_hi:[1,0]
	v_pk_add_f32 v[172:173], v[112:113], 0 op_sel_hi:[1,0]
	v_lshlrev_b64 v[112:113], 2, v[162:163]
	v_lshl_add_u64 v[114:115], s[76:77], 0, v[114:115]
	v_lshlrev_b64 v[116:117], 11, v[174:175]
	v_lshl_add_u64 v[162:163], v[114:115], 0, v[112:113]
	v_lshl_add_u64 v[114:115], s[78:79], 0, v[116:117]
	v_pk_add_f32 v[126:127], v[126:127], 0 op_sel_hi:[1,0]
	v_pk_add_f32 v[124:125], v[124:125], 0 op_sel_hi:[1,0]
	v_pk_add_f32 v[122:123], v[122:123], 0 op_sel_hi:[1,0]
	v_pk_add_f32 v[164:165], v[120:121], 0 op_sel_hi:[1,0]
	v_pk_add_f32 v[166:167], v[118:119], 0 op_sel_hi:[1,0]
	v_lshl_add_u64 v[176:177], v[114:115], 0, v[146:147]
	v_pk_add_f32 v[110:111], v[110:111], 0 op_sel_hi:[1,0]
	v_pk_add_f32 v[108:109], v[108:109], 0 op_sel_hi:[1,0]
	v_pk_add_f32 v[106:107], v[106:107], 0 op_sel_hi:[1,0]
	v_pk_add_f32 v[104:105], v[104:105], 0 op_sel_hi:[1,0]
	v_pk_add_f32 v[94:95], v[94:95], 0 op_sel_hi:[1,0]
	v_pk_add_f32 v[92:93], v[92:93], 0 op_sel_hi:[1,0]
	v_pk_add_f32 v[90:91], v[90:91], 0 op_sel_hi:[1,0]
	v_pk_add_f32 v[88:89], v[88:89], 0 op_sel_hi:[1,0]
	v_pk_add_f32 v[78:79], v[78:79], 0 op_sel_hi:[1,0]
	v_pk_add_f32 v[76:77], v[76:77], 0 op_sel_hi:[1,0]
	v_pk_add_f32 v[74:75], v[74:75], 0 op_sel_hi:[1,0]
	v_pk_add_f32 v[72:73], v[72:73], 0 op_sel_hi:[1,0]
	v_pk_add_f32 v[62:63], v[62:63], 0 op_sel_hi:[1,0]
	v_pk_add_f32 v[60:61], v[60:61], 0 op_sel_hi:[1,0]
	v_pk_add_f32 v[58:59], v[58:59], 0 op_sel_hi:[1,0]
	v_pk_add_f32 v[56:57], v[56:57], 0 op_sel_hi:[1,0]
	v_pk_add_f32 v[46:47], v[46:47], 0 op_sel_hi:[1,0]
	v_pk_add_f32 v[44:45], v[44:45], 0 op_sel_hi:[1,0]
	v_pk_add_f32 v[42:43], v[42:43], 0 op_sel_hi:[1,0]
	v_pk_add_f32 v[40:41], v[40:41], 0 op_sel_hi:[1,0]
	v_pk_add_f32 v[30:31], v[30:31], 0 op_sel_hi:[1,0]
	v_pk_add_f32 v[28:29], v[28:29], 0 op_sel_hi:[1,0]
	v_pk_add_f32 v[26:27], v[26:27], 0 op_sel_hi:[1,0]
	v_pk_add_f32 v[24:25], v[24:25], 0 op_sel_hi:[1,0]
	v_pk_add_f32 v[14:15], v[14:15], 0 op_sel_hi:[1,0]
	v_pk_add_f32 v[12:13], v[12:13], 0 op_sel_hi:[1,0]
	v_pk_add_f32 v[10:11], v[10:11], 0 op_sel_hi:[1,0]
	v_pk_add_f32 v[8:9], v[8:9], 0 op_sel_hi:[1,0]
	s_andn2_b64 vcc, exec, s[0:1]
	s_mov_b64 s[0:1], -1
	s_waitcnt vmcnt(0)
	v_lshlrev_b32_e32 v114, 16, v154
	v_and_b32_e32 v115, 0xffff0000, v154
	v_lshlrev_b32_e32 v116, 16, v155
	v_and_b32_e32 v117, 0xffff0000, v155
	v_lshlrev_b32_e32 v118, 16, v156
	v_and_b32_e32 v119, 0xffff0000, v156
	v_lshlrev_b32_e32 v120, 16, v157
	v_and_b32_e32 v121, 0xffff0000, v157
	v_lshlrev_b32_e32 v154, 16, v158
	v_and_b32_e32 v155, 0xffff0000, v158
	v_lshlrev_b32_e32 v156, 16, v159
	v_pk_add_f32 v[116:117], v[126:127], v[116:117]
	v_pk_add_f32 v[114:115], v[124:125], v[114:115]
	v_pk_add_f32 v[120:121], v[122:123], v[120:121]
	v_pk_add_f32 v[118:119], v[164:165], v[118:119]
	v_and_b32_e32 v157, 0xffff0000, v159
	global_store_dwordx4 v[162:163], v[114:117], off nt
	global_store_dwordx4 v[162:163], v[118:121], off offset:16 nt
	v_lshlrev_b32_e32 v122, 16, v160
	v_and_b32_e32 v123, 0xffff0000, v160
	v_lshlrev_b32_e32 v124, 16, v161
	v_and_b32_e32 v125, 0xffff0000, v161
	v_pk_add_f32 v[120:121], v[166:167], v[156:157]
	v_pk_add_f32 v[118:119], v[168:169], v[154:155]
	global_load_dwordx4 v[114:117], v[176:177], off nt
	v_pk_add_f32 v[124:125], v[170:171], v[124:125]
	v_pk_add_f32 v[122:123], v[172:173], v[122:123]
	global_store_dwordx4 v[162:163], v[118:121], off offset:512 nt
	global_store_dwordx4 v[162:163], v[122:125], off offset:528 nt
	global_load_dwordx4 v[118:121], v[176:177], off offset:256 nt
	v_or_b32_e32 v156, 32, v144
	v_ashrrev_i32_e32 v157, 31, v156
	v_pk_add_f32 v[126:127], v[98:99], 0 op_sel_hi:[1,0]
	v_pk_add_f32 v[154:155], v[96:97], 0 op_sel_hi:[1,0]
	v_lshlrev_b64 v[96:97], 12, v[174:175]
	v_lshlrev_b64 v[98:99], 11, v[156:157]
	v_lshl_add_u64 v[96:97], s[76:77], 0, v[96:97]
	v_lshl_add_u64 v[98:99], s[78:79], 0, v[98:99]
	v_pk_add_f32 v[122:123], v[102:103], 0 op_sel_hi:[1,0]
	v_pk_add_f32 v[124:125], v[100:101], 0 op_sel_hi:[1,0]
	v_lshl_add_u64 v[158:159], v[96:97], 0, v[112:113]
	v_lshl_add_u64 v[160:161], v[98:99], 0, v[146:147]
	s_waitcnt vmcnt(3)
	v_lshlrev_b32_e32 v96, 16, v114
	v_and_b32_e32 v97, 0xffff0000, v114
	v_lshlrev_b32_e32 v98, 16, v115
	v_and_b32_e32 v99, 0xffff0000, v115
	v_lshlrev_b32_e32 v100, 16, v116
	v_and_b32_e32 v101, 0xffff0000, v116
	v_lshlrev_b32_e32 v102, 16, v117
	v_and_b32_e32 v103, 0xffff0000, v117
	v_pk_add_f32 v[98:99], v[110:111], v[98:99]
	v_pk_add_f32 v[96:97], v[108:109], v[96:97]
	v_pk_add_f32 v[102:103], v[106:107], v[102:103]
	v_pk_add_f32 v[100:101], v[104:105], v[100:101]
	s_waitcnt vmcnt(0)
; __device__ __forceinline__ unsigned pk2(float lo, float hi) { f32x2_t v = {lo, hi}; bf16x2_t b = __builtin_convertvector(v, bf16x2_t); return __builtin_bit_cast(unsigned, b); }
;     __device__ __forceinline__ float rowscale(int r) const { return rsmode == 1 ? rs[r] : (rsmode == 2 ? rsqrtf((float)rs64[r] * (RSS_UNFIX * rsinv) + EPS) : 1.f); }
;     __device__ __forceinline__ void operator()(const pg8::f32x4 (&acc)[2][2][4][2], const pg8::Unit& u, int wr, int wc, int fr, int fq) const {
;     ...
;             for (int p = 0; p < 16; ++p) {
;                 const int g = p >> 1, bj = p & 1, ai = g >> 2, m = g & 3, r = row0 + ai * 128 + m * 16, c = col0 + bj * 128;
;                 if (p < 15) {
;                     const int gn = (p + 1) >> 1, rn = row0 + (gn >> 2) * 128 + (gn & 3) * 16, cn = col0 + ((p + 1) & 1) * 128;
;                     if (hasF) nb2 = *(const u32x4*)(base2 + (size_t)rn * 1024 + cn);
;                     nbb = *(const u32x4*)(baseb + (size_t)rn * 1024 + cn);
;                     if (bj == 1) nsc = rowscale(rn);
;                 }
;                 const f32x4 r0 = {bflo(cbb.x), bfhi(cbb.x), bflo(cbb.y), bfhi(cbb.y)}, r1 = {bflo(cbb.z), bfhi(cbb.z), bflo(cbb.w), bfhi(cbb.w)};
;                 const f32x4 q0 = {bflo(cb2.x), bfhi(cb2.x), bflo(cb2.y), bfhi(cb2.y)}, q1 = {bflo(cb2.z), bfhi(cb2.z), bflo(cb2.w), bfhi(cb2.w)};
;                 const f32x4 v0 = acc[ai][bj][m][0] * csc + q0 + r0, v1 = acc[ai][bj][m][1] * csc + q1 + r1;
;                 if (outF) {
;                     float* op = out + (size_t)r * 1024 + c;
;                     *(f32x4*)op = v0; *(f32x4*)(op + 4) = v1;
;                 } else {
;                     u32x4 w; w.x = pk2(v0[0], v0[1]); w.y = pk2(v0[2], v0[3]); w.z = pk2(v1[0], v1[1]); w.w = pk2(v1[2], v1[3]);
;                     *(u32x4*)(O + (size_t)r * 1024 + c) = w;
;                     ss += (v0[0] * v0[0] + v0[1] * v0[1]) + (v0[2] * v0[2] + v0[3] * v0[3]) + (v1[0] * v1[0] + v1[1] * v1[1]) + (v1[2] * v1[2] + v1[3] * v1[3]);
;                     if (bj == 1) {
;                         ss += __shfl_xor(ss, 16); ss += __shfl_xor(ss, 32);
;                         if (fq == 0) atomicAdd(rss + r, (u64)(ss * RSS_FIX));
;                         ss = 0.f;
;                     }
;                 }
;                 cb2 = nb2; cbb = nbb;
	v_lshlrev_b32_e32 v104, 16, v118
	v_and_b32_e32 v105, 0xffff0000, v118
	v_lshlrev_b32_e32 v106, 16, v119
	v_and_b32_e32 v107, 0xffff0000, v119
	global_store_dwordx4 v[158:159], v[96:99], off nt
	global_store_dwordx4 v[158:159], v[100:103], off offset:16 nt
	v_lshlrev_b32_e32 v108, 16, v120
	v_and_b32_e32 v109, 0xffff0000, v120
	v_lshlrev_b32_e32 v110, 16, v121
	v_and_b32_e32 v111, 0xffff0000, v121
	v_pk_add_f32 v[102:103], v[122:123], v[106:107]
	v_pk_add_f32 v[100:101], v[124:125], v[104:105]
	global_load_dwordx4 v[96:99], v[160:161], off nt
	v_pk_add_f32 v[106:107], v[126:127], v[110:111]
	v_pk_add_f32 v[104:105], v[154:155], v[108:109]
	global_store_dwordx4 v[158:159], v[100:103], off offset:512 nt
	global_store_dwordx4 v[158:159], v[104:107], off offset:528 nt
	global_load_dwordx4 v[100:103], v[160:161], off offset:256 nt
	v_or_b32_e32 v114, 48, v144
	v_ashrrev_i32_e32 v115, 31, v114
	v_pk_add_f32 v[108:109], v[82:83], 0 op_sel_hi:[1,0]
	v_pk_add_f32 v[110:111], v[80:81], 0 op_sel_hi:[1,0]
	v_lshlrev_b64 v[80:81], 12, v[156:157]
	v_lshlrev_b64 v[82:83], 11, v[114:115]
	v_lshl_add_u64 v[80:81], s[76:77], 0, v[80:81]
	v_lshl_add_u64 v[82:83], s[78:79], 0, v[82:83]
	v_pk_add_f32 v[104:105], v[86:87], 0 op_sel_hi:[1,0]
	v_pk_add_f32 v[106:107], v[84:85], 0 op_sel_hi:[1,0]
	v_lshl_add_u64 v[116:117], v[80:81], 0, v[112:113]
	v_lshl_add_u64 v[118:119], v[82:83], 0, v[146:147]
	s_waitcnt vmcnt(3)
	v_lshlrev_b32_e32 v80, 16, v96
	v_and_b32_e32 v81, 0xffff0000, v96
	v_lshlrev_b32_e32 v82, 16, v97
	v_and_b32_e32 v83, 0xffff0000, v97
	v_lshlrev_b32_e32 v84, 16, v98
	v_and_b32_e32 v85, 0xffff0000, v98
	v_lshlrev_b32_e32 v86, 16, v99
	v_and_b32_e32 v87, 0xffff0000, v99
	v_pk_add_f32 v[82:83], v[94:95], v[82:83]
	v_pk_add_f32 v[80:81], v[92:93], v[80:81]
	v_pk_add_f32 v[86:87], v[90:91], v[86:87]
	v_pk_add_f32 v[84:85], v[88:89], v[84:85]
	s_waitcnt vmcnt(0)
	v_lshlrev_b32_e32 v88, 16, v100
	v_and_b32_e32 v89, 0xffff0000, v100
	v_lshlrev_b32_e32 v90, 16, v101
	v_and_b32_e32 v91, 0xffff0000, v101
	global_store_dwordx4 v[116:117], v[80:83], off nt
	global_store_dwordx4 v[116:117], v[84:87], off offset:16 nt
	v_lshlrev_b32_e32 v92, 16, v102
	v_and_b32_e32 v93, 0xffff0000, v102
	v_lshlrev_b32_e32 v94, 16, v103
	v_and_b32_e32 v95, 0xffff0000, v103
	v_pk_add_f32 v[86:87], v[104:105], v[90:91]
	v_pk_add_f32 v[84:85], v[106:107], v[88:89]
	global_load_dwordx4 v[80:83], v[118:119], off nt
	v_pk_add_f32 v[90:91], v[108:109], v[94:95]
	v_pk_add_f32 v[88:89], v[110:111], v[92:93]
	global_store_dwordx4 v[116:117], v[84:87], off offset:512 nt
	global_store_dwordx4 v[116:117], v[88:91], off offset:528 nt
	global_load_dwordx4 v[84:87], v[118:119], off offset:256 nt
	v_add_u32_e32 v96, 0x80, v144
	v_ashrrev_i32_e32 v97, 31, v96
	v_pk_add_f32 v[92:93], v[66:67], 0 op_sel_hi:[1,0]
	v_pk_add_f32 v[94:95], v[64:65], 0 op_sel_hi:[1,0]
	v_lshlrev_b64 v[64:65], 12, v[114:115]
	v_lshlrev_b64 v[66:67], 11, v[96:97]
	v_lshl_add_u64 v[64:65], s[76:77], 0, v[64:65]
	v_lshl_add_u64 v[66:67], s[78:79], 0, v[66:67]
	v_pk_add_f32 v[88:89], v[70:71], 0 op_sel_hi:[1,0]
	v_pk_add_f32 v[90:91], v[68:69], 0 op_sel_hi:[1,0]
	v_lshl_add_u64 v[98:99], v[64:65], 0, v[112:113]
	v_lshl_add_u64 v[100:101], v[66:67], 0, v[146:147]
	s_waitcnt vmcnt(3)
	v_lshlrev_b32_e32 v64, 16, v80
	v_and_b32_e32 v65, 0xffff0000, v80
	v_lshlrev_b32_e32 v66, 16, v81
	v_and_b32_e32 v67, 0xffff0000, v81
	v_lshlrev_b32_e32 v68, 16, v82
	v_and_b32_e32 v69, 0xffff0000, v82
	v_lshlrev_b32_e32 v70, 16, v83
	v_and_b32_e32 v71, 0xffff0000, v83
	v_pk_add_f32 v[66:67], v[78:79], v[66:67]
	v_pk_add_f32 v[64:65], v[76:77], v[64:65]
	v_pk_add_f32 v[70:71], v[74:75], v[70:71]
	v_pk_add_f32 v[68:69], v[72:73], v[68:69]
	s_waitcnt vmcnt(0)
	v_lshlrev_b32_e32 v72, 16, v84
	v_and_b32_e32 v73, 0xffff0000, v84
	v_lshlrev_b32_e32 v74, 16, v85
	v_and_b32_e32 v75, 0xffff0000, v85
	global_store_dwordx4 v[98:99], v[64:67], off nt
	global_store_dwordx4 v[98:99], v[68:71], off offset:16 nt
	v_lshlrev_b32_e32 v76, 16, v86
	v_and_b32_e32 v77, 0xffff0000, v86
	v_lshlrev_b32_e32 v78, 16, v87
	v_and_b32_e32 v79, 0xffff0000, v87
	v_pk_add_f32 v[70:71], v[88:89], v[74:75]
	v_pk_add_f32 v[68:69], v[90:91], v[72:73]
	global_load_dwordx4 v[64:67], v[100:101], off nt
	v_pk_add_f32 v[74:75], v[92:93], v[78:79]
	v_pk_add_f32 v[72:73], v[94:95], v[76:77]
	global_store_dwordx4 v[98:99], v[68:71], off offset:512 nt
	global_store_dwordx4 v[98:99], v[72:75], off offset:528 nt
	global_load_dwordx4 v[68:71], v[100:101], off offset:256 nt
	v_add_u32_e32 v80, 0x90, v144
	v_ashrrev_i32_e32 v81, 31, v80
	v_pk_add_f32 v[76:77], v[50:51], 0 op_sel_hi:[1,0]
	v_pk_add_f32 v[78:79], v[48:49], 0 op_sel_hi:[1,0]
	v_lshlrev_b64 v[48:49], 12, v[96:97]
	v_lshlrev_b64 v[50:51], 11, v[80:81]
	v_lshl_add_u64 v[48:49], s[76:77], 0, v[48:49]
	v_lshl_add_u64 v[50:51], s[78:79], 0, v[50:51]
	v_pk_add_f32 v[72:73], v[54:55], 0 op_sel_hi:[1,0]
	v_pk_add_f32 v[74:75], v[52:53], 0 op_sel_hi:[1,0]
	v_lshl_add_u64 v[82:83], v[48:49], 0, v[112:113]
	v_lshl_add_u64 v[84:85], v[50:51], 0, v[146:147]
	s_waitcnt vmcnt(3)
	v_lshlrev_b32_e32 v48, 16, v64
	v_and_b32_e32 v49, 0xffff0000, v64
	v_lshlrev_b32_e32 v50, 16, v65
	v_and_b32_e32 v51, 0xffff0000, v65
	v_lshlrev_b32_e32 v52, 16, v66
	v_and_b32_e32 v53, 0xffff0000, v66
	v_lshlrev_b32_e32 v54, 16, v67
	v_and_b32_e32 v55, 0xffff0000, v67
	v_pk_add_f32 v[50:51], v[62:63], v[50:51]
	v_pk_add_f32 v[48:49], v[60:61], v[48:49]
	v_pk_add_f32 v[54:55], v[58:59], v[54:55]
	v_pk_add_f32 v[52:53], v[56:57], v[52:53]
	s_waitcnt vmcnt(0)
; template <class Epi, class Sched, bool ALIGN_EPI = false, bool SP2 = false>
; __device__ __forceinline__ void gemm_phase(PG8_LAS unsigned char* lds, const Gemm g, const Sched& S, const Epi& E) {
;     ...
;         if constexpr (!Epi::AFTER_DRAIN) { if (partial) E.mid(acc, cur, wr, fr); else { E(acc, cur, wr, wc, fr, fq); S.done(cur); } }
;     __device__ __forceinline__ void operator()(const pg8::f32x4 (&acc)[2][2][4][2], const pg8::Unit& u, int wr, int wc, int fr, int fq) const {
;     ...
;             for (int p = 0; p < 16; ++p) {
;                 const int g = p >> 1, bj = p & 1, ai = g >> 2, m = g & 3, r = row0 + ai * 128 + m * 16, c = col0 + bj * 128;
;                 if (p < 15) {
;                     const int gn = (p + 1) >> 1, rn = row0 + (gn >> 2) * 128 + (gn & 3) * 16, cn = col0 + ((p + 1) & 1) * 128;
;                     if (hasF) nb2 = *(const u32x4*)(base2 + (size_t)rn * 1024 + cn);
;                     nbb = *(const u32x4*)(baseb + (size_t)rn * 1024 + cn);
;                     if (bj == 1) nsc = rowscale(rn);
;                 }
;                 const f32x4 r0 = {bflo(cbb.x), bfhi(cbb.x), bflo(cbb.y), bfhi(cbb.y)}, r1 = {bflo(cbb.z), bfhi(cbb.z), bflo(cbb.w), bfhi(cbb.w)};
;                 const f32x4 q0 = {bflo(cb2.x), bfhi(cb2.x), bflo(cb2.y), bfhi(cb2.y)}, q1 = {bflo(cb2.z), bfhi(cb2.z), bflo(cb2.w), bfhi(cb2.w)};
;                 const f32x4 v0 = acc[ai][bj][m][0] * csc + q0 + r0, v1 = acc[ai][bj][m][1] * csc + q1 + r1;
;                 if (outF) {
;                     float* op = out + (size_t)r * 1024 + c;
;                     *(f32x4*)op = v0; *(f32x4*)(op + 4) = v1;
;                 } else {
;                     u32x4 w; w.x = pk2(v0[0], v0[1]); w.y = pk2(v0[2], v0[3]); w.z = pk2(v1[0], v1[1]); w.w = pk2(v1[2], v1[3]);
;                     *(u32x4*)(O + (size_t)r * 1024 + c) = w;
;                     ss += (v0[0] * v0[0] + v0[1] * v0[1]) + (v0[2] * v0[2] + v0[3] * v0[3]) + (v1[0] * v1[0] + v1[1] * v1[1]) + (v1[2] * v1[2] + v1[3] * v1[3]);
;                     if (bj == 1) {
;                         ss += __shfl_xor(ss, 16); ss += __shfl_xor(ss, 32);
;                         if (fq == 0) atomicAdd(rss + r, (u64)(ss * RSS_FIX));
;                         ss = 0.f;
;                     }
;                 }
;                 cb2 = nb2; cbb = nbb;
;                 if (bj == 1) csc = nsc;
;             }
	v_lshlrev_b32_e32 v56, 16, v68
	v_and_b32_e32 v57, 0xffff0000, v68
	v_lshlrev_b32_e32 v58, 16, v69
	v_and_b32_e32 v59, 0xffff0000, v69
	global_store_dwordx4 v[82:83], v[48:51], off nt
	global_store_dwordx4 v[82:83], v[52:55], off offset:16 nt
	v_lshlrev_b32_e32 v60, 16, v70
	v_and_b32_e32 v61, 0xffff0000, v70
	v_lshlrev_b32_e32 v62, 16, v71
	v_and_b32_e32 v63, 0xffff0000, v71
	v_pk_add_f32 v[54:55], v[72:73], v[58:59]
	v_pk_add_f32 v[52:53], v[74:75], v[56:57]
	global_load_dwordx4 v[48:51], v[84:85], off nt
	v_pk_add_f32 v[58:59], v[76:77], v[62:63]
	v_pk_add_f32 v[56:57], v[78:79], v[60:61]
	global_store_dwordx4 v[82:83], v[52:55], off offset:512 nt
	global_store_dwordx4 v[82:83], v[56:59], off offset:528 nt
	global_load_dwordx4 v[52:55], v[84:85], off offset:256 nt
	v_add_u32_e32 v64, 0xa0, v144
	v_ashrrev_i32_e32 v65, 31, v64
	v_pk_add_f32 v[60:61], v[34:35], 0 op_sel_hi:[1,0]
	v_pk_add_f32 v[62:63], v[32:33], 0 op_sel_hi:[1,0]
	v_lshlrev_b64 v[32:33], 12, v[80:81]
	v_lshlrev_b64 v[34:35], 11, v[64:65]
	v_lshl_add_u64 v[32:33], s[76:77], 0, v[32:33]
	v_lshl_add_u64 v[34:35], s[78:79], 0, v[34:35]
	v_pk_add_f32 v[56:57], v[38:39], 0 op_sel_hi:[1,0]
	v_pk_add_f32 v[58:59], v[36:37], 0 op_sel_hi:[1,0]
	v_lshl_add_u64 v[66:67], v[32:33], 0, v[112:113]
	v_lshl_add_u64 v[68:69], v[34:35], 0, v[146:147]
	s_waitcnt vmcnt(3)
	v_lshlrev_b32_e32 v32, 16, v48
	v_and_b32_e32 v33, 0xffff0000, v48
	v_lshlrev_b32_e32 v34, 16, v49
	v_and_b32_e32 v35, 0xffff0000, v49
	v_lshlrev_b32_e32 v36, 16, v50
	v_and_b32_e32 v37, 0xffff0000, v50
	v_lshlrev_b32_e32 v38, 16, v51
	v_and_b32_e32 v39, 0xffff0000, v51
	v_pk_add_f32 v[34:35], v[46:47], v[34:35]
	v_pk_add_f32 v[32:33], v[44:45], v[32:33]
	v_pk_add_f32 v[38:39], v[42:43], v[38:39]
	v_pk_add_f32 v[36:37], v[40:41], v[36:37]
	s_waitcnt vmcnt(0)
	v_lshlrev_b32_e32 v40, 16, v52
	v_and_b32_e32 v41, 0xffff0000, v52
	v_lshlrev_b32_e32 v42, 16, v53
	v_and_b32_e32 v43, 0xffff0000, v53
	global_store_dwordx4 v[66:67], v[32:35], off nt
	global_store_dwordx4 v[66:67], v[36:39], off offset:16 nt
	v_lshlrev_b32_e32 v44, 16, v54
	v_and_b32_e32 v45, 0xffff0000, v54
	v_lshlrev_b32_e32 v46, 16, v55
	v_and_b32_e32 v47, 0xffff0000, v55
	v_pk_add_f32 v[38:39], v[56:57], v[42:43]
	v_pk_add_f32 v[36:37], v[58:59], v[40:41]
	global_load_dwordx4 v[32:35], v[68:69], off nt
	v_pk_add_f32 v[42:43], v[60:61], v[46:47]
	v_pk_add_f32 v[40:41], v[62:63], v[44:45]
	global_store_dwordx4 v[66:67], v[36:39], off offset:512 nt
	global_store_dwordx4 v[66:67], v[40:43], off offset:528 nt
	global_load_dwordx4 v[36:39], v[68:69], off offset:256 nt
	v_add_u32_e32 v48, 0xb0, v144
	v_ashrrev_i32_e32 v49, 31, v48
	v_pk_add_f32 v[44:45], v[18:19], 0 op_sel_hi:[1,0]
	v_pk_add_f32 v[46:47], v[16:17], 0 op_sel_hi:[1,0]
	v_lshlrev_b64 v[16:17], 12, v[64:65]
	v_lshlrev_b64 v[18:19], 11, v[48:49]
	v_lshl_add_u64 v[16:17], s[76:77], 0, v[16:17]
	v_lshl_add_u64 v[18:19], s[78:79], 0, v[18:19]
	v_pk_add_f32 v[40:41], v[22:23], 0 op_sel_hi:[1,0]
	v_pk_add_f32 v[42:43], v[20:21], 0 op_sel_hi:[1,0]
	v_lshl_add_u64 v[50:51], v[16:17], 0, v[112:113]
	v_lshl_add_u64 v[52:53], v[18:19], 0, v[146:147]
	s_waitcnt vmcnt(3)
	v_lshlrev_b32_e32 v16, 16, v32
	v_and_b32_e32 v17, 0xffff0000, v32
	v_lshlrev_b32_e32 v18, 16, v33
	v_and_b32_e32 v19, 0xffff0000, v33
	v_lshlrev_b32_e32 v20, 16, v34
	v_and_b32_e32 v21, 0xffff0000, v34
	v_lshlrev_b32_e32 v22, 16, v35
	v_and_b32_e32 v23, 0xffff0000, v35
	v_pk_add_f32 v[18:19], v[30:31], v[18:19]
	v_pk_add_f32 v[16:17], v[28:29], v[16:17]
	v_pk_add_f32 v[22:23], v[26:27], v[22:23]
	v_pk_add_f32 v[20:21], v[24:25], v[20:21]
	s_waitcnt vmcnt(0)
	v_lshlrev_b32_e32 v24, 16, v36
	v_and_b32_e32 v25, 0xffff0000, v36
	v_lshlrev_b32_e32 v26, 16, v37
	v_and_b32_e32 v27, 0xffff0000, v37
	global_store_dwordx4 v[50:51], v[16:19], off nt
	global_store_dwordx4 v[50:51], v[20:23], off offset:16 nt
	v_lshlrev_b32_e32 v28, 16, v38
	v_and_b32_e32 v29, 0xffff0000, v38
	v_lshlrev_b32_e32 v30, 16, v39
	v_and_b32_e32 v31, 0xffff0000, v39
	v_pk_add_f32 v[22:23], v[40:41], v[26:27]
	v_pk_add_f32 v[20:21], v[42:43], v[24:25]
	global_load_dwordx4 v[16:19], v[52:53], off nt
	v_pk_add_f32 v[26:27], v[44:45], v[30:31]
	v_pk_add_f32 v[24:25], v[46:47], v[28:29]
	global_store_dwordx4 v[50:51], v[20:23], off offset:512 nt
	global_store_dwordx4 v[50:51], v[24:27], off offset:528 nt
	global_load_dwordx4 v[20:23], v[52:53], off offset:256 nt
	v_pk_add_f32 v[30:31], v[0:1], 0 op_sel_hi:[1,0]
	v_lshlrev_b64 v[0:1], 12, v[48:49]
	v_lshl_add_u64 v[0:1], s[76:77], 0, v[0:1]
	v_pk_add_f32 v[24:25], v[6:7], 0 op_sel_hi:[1,0]
	v_pk_add_f32 v[26:27], v[4:5], 0 op_sel_hi:[1,0]
	v_pk_add_f32 v[28:29], v[2:3], 0 op_sel_hi:[1,0]
	v_lshl_add_u64 v[32:33], v[0:1], 0, v[112:113]
	s_waitcnt vmcnt(3)
	v_lshlrev_b32_e32 v0, 16, v16
	v_and_b32_e32 v1, 0xffff0000, v16
	v_lshlrev_b32_e32 v2, 16, v17
	v_and_b32_e32 v3, 0xffff0000, v17
	v_lshlrev_b32_e32 v4, 16, v18
	v_and_b32_e32 v5, 0xffff0000, v18
	v_lshlrev_b32_e32 v6, 16, v19
	v_and_b32_e32 v7, 0xffff0000, v19
	v_pk_add_f32 v[2:3], v[14:15], v[2:3]
	v_pk_add_f32 v[0:1], v[12:13], v[0:1]
	v_pk_add_f32 v[6:7], v[10:11], v[6:7]
	v_pk_add_f32 v[4:5], v[8:9], v[4:5]
	s_waitcnt vmcnt(0)
	v_lshlrev_b32_e32 v8, 16, v20
	v_and_b32_e32 v9, 0xffff0000, v20
	v_lshlrev_b32_e32 v10, 16, v21
	v_and_b32_e32 v11, 0xffff0000, v21
	v_lshlrev_b32_e32 v12, 16, v22
	v_and_b32_e32 v13, 0xffff0000, v22
	v_lshlrev_b32_e32 v14, 16, v23
	v_and_b32_e32 v15, 0xffff0000, v23
	global_store_dwordx4 v[32:33], v[0:3], off nt
	global_store_dwordx4 v[32:33], v[4:7], off offset:16 nt
	s_nop 0
	v_pk_add_f32 v[2:3], v[24:25], v[10:11]
	v_pk_add_f32 v[0:1], v[26:27], v[8:9]
	v_pk_add_f32 v[6:7], v[28:29], v[14:15]
	v_pk_add_f32 v[4:5], v[30:31], v[12:13]
	global_store_dwordx4 v[32:33], v[0:3], off offset:512 nt
	global_store_dwordx4 v[32:33], v[4:7], off offset:528 nt
	s_cbranch_vccnz .LBB0_1031
	s_andn2_b64 vcc, exec, s[2:3]
	s_cbranch_vccnz .LBB0_1030
	s_barrier
	s_branch .LBB0_1030
